# grid barrier: every workgroup's L1 invalidate is issued at arrival (leader: together with its L2 write-back); nobody loads between arrival and release
# baseline (speedup 1.0000x reference)
; __device__ __forceinline__ unsigned xb_add(unsigned* p, unsigned v) { return __hip_atomic_fetch_add(p, v, __ATOMIC_RELAXED, __HIP_MEMORY_SCOPE_AGENT); }
; __device__ __forceinline__ void xcd_barrier(const XcdBarrier& b) {
;     ...
;         const unsigned old = xb_add(&bar[XB_XSUB(b.x)], 1u);
;         const unsigned gen = old / nloc;
;         if (old + 1u == (gen + 1u) * nloc) {
;             __builtin_amdgcn_fence(__ATOMIC_RELEASE, "agent");
;             asm volatile("s_waitcnt vmcnt(0)" ::: "memory");
;             const unsigned og = xb_add(&bar[XB_TOP], 1u);
.LBB0_115:
	s_andn2_saveexec_b64 s[6:7], s[10:11]
	s_cbranch_execz .LBB0_135
	s_mov_b64 s[10:11], exec
	buffer_wbl2 sc1
	buffer_inv sc1
	s_waitcnt lgkmcnt(0)
	s_waitcnt vmcnt(0)
	v_mbcnt_lo_u32_b32 v1, s10, 0
	v_mbcnt_hi_u32_b32 v1, s11, v1
	v_cmp_eq_u32_e32 vcc, 0, v1
	s_and_saveexec_b64 s[12:13], vcc
	s_cbranch_execz .LBB0_118
	s_bcnt1_i32_b64 s6, s[10:11]
	v_mov_b32_e32 v2, 0x3000
	v_mov_b32_e32 v3, s6
	global_atomic_add v2, v2, v3, s[26:27] offset:1024 sc0

; __device__ __forceinline__ unsigned xb_add(unsigned* p, unsigned v) { return __hip_atomic_fetch_add(p, v, __ATOMIC_RELAXED, __HIP_MEMORY_SCOPE_AGENT); }
; __device__ __forceinline__ void xcd_barrier(const XcdBarrier& b) {
;     ...
;             __builtin_amdgcn_fence(__ATOMIC_ACQUIRE, "agent");
;             xb_add(&bar[XB_XGEN(b.x)], 1u);
.LBB0_132:
	s_or_b64 exec, exec, s[10:11]
	s_mov_b64 s[10:11], exec
	v_mbcnt_lo_u32_b32 v0, s10, 0
	v_mbcnt_hi_u32_b32 v0, s11, v0
	v_cmp_eq_u32_e32 vcc, 0, v0
	s_waitcnt vmcnt(0)
	s_and_saveexec_b64 s[12:13], vcc
	s_cbranch_execz .LBB0_134
	s_bcnt1_i32_b64 s6, s[10:11]
	v_mov_b32_e32 v0, 0x2000
	v_mov_b32_e32 v1, s6
	global_atomic_add v0, v1, s[8:9] offset:1024

; __device__ __forceinline__ unsigned xb_add(unsigned* p, unsigned v) { return __hip_atomic_fetch_add(p, v, __ATOMIC_RELAXED, __HIP_MEMORY_SCOPE_AGENT); }
; __device__ __forceinline__ void xcd_barrier(const XcdBarrier& b) {
;     ...
;         const unsigned old = xb_add(&bar[XB_XSUB(b.x)], 1u);
;         const unsigned gen = old / nloc;
;         if (old + 1u == (gen + 1u) * nloc) {
;             __builtin_amdgcn_fence(__ATOMIC_RELEASE, "agent");
;             asm volatile("s_waitcnt vmcnt(0)" ::: "memory");
;             const unsigned og = xb_add(&bar[XB_TOP], 1u);
.LBB0_471:
	s_andn2_saveexec_b64 s[6:7], s[8:9]
	s_cbranch_execz .LBB0_491
	s_mov_b64 s[8:9], exec
	buffer_wbl2 sc1
	buffer_inv sc1
	s_waitcnt lgkmcnt(0)
	s_waitcnt vmcnt(0)
	v_mbcnt_lo_u32_b32 v1, s8, 0
	v_mbcnt_hi_u32_b32 v1, s9, v1
	v_cmp_eq_u32_e32 vcc, 0, v1
	s_and_saveexec_b64 s[10:11], vcc
	s_cbranch_execz .LBB0_474
	s_bcnt1_i32_b64 s6, s[8:9]
	v_mov_b32_e32 v2, 0x3000
	v_mov_b32_e32 v3, s6
	global_atomic_add v2, v2, v3, s[26:27] offset:1024 sc0

; __device__ __forceinline__ unsigned xb_add(unsigned* p, unsigned v) { return __hip_atomic_fetch_add(p, v, __ATOMIC_RELAXED, __HIP_MEMORY_SCOPE_AGENT); }
; __device__ __forceinline__ void xcd_barrier(const XcdBarrier& b) {
;     ...
;             __builtin_amdgcn_fence(__ATOMIC_ACQUIRE, "agent");
;             xb_add(&bar[XB_XGEN(b.x)], 1u);
.LBB0_488:
	s_or_b64 exec, exec, s[8:9]
	s_mov_b64 s[8:9], exec
	v_mbcnt_lo_u32_b32 v0, s8, 0
	v_mbcnt_hi_u32_b32 v0, s9, v0
	v_cmp_eq_u32_e32 vcc, 0, v0
	s_waitcnt vmcnt(0)
	s_and_saveexec_b64 s[10:11], vcc
	s_cbranch_execz .LBB0_490
	s_bcnt1_i32_b64 s6, s[8:9]
	v_mov_b32_e32 v0, 0x2000
	v_mov_b32_e32 v1, s6
	global_atomic_add v0, v1, s[4:5] offset:1024

; __device__ __forceinline__ unsigned xb_add(unsigned* p, unsigned v) { return __hip_atomic_fetch_add(p, v, __ATOMIC_RELAXED, __HIP_MEMORY_SCOPE_AGENT); }
; __device__ __forceinline__ void xcd_barrier(const XcdBarrier& b) {
;     ...
;         const unsigned old = xb_add(&bar[XB_XSUB(b.x)], 1u);
;         const unsigned gen = old / nloc;
;         if (old + 1u == (gen + 1u) * nloc) {
;             __builtin_amdgcn_fence(__ATOMIC_RELEASE, "agent");
;             asm volatile("s_waitcnt vmcnt(0)" ::: "memory");
;             const unsigned og = xb_add(&bar[XB_TOP], 1u);
.LBB0_982:
	s_andn2_saveexec_b64 s[6:7], s[6:7]
	s_cbranch_execz .LBB0_1002
	s_mov_b64 s[6:7], exec
	buffer_wbl2 sc1
	buffer_inv sc1
	s_waitcnt lgkmcnt(0)
	s_waitcnt vmcnt(0)
	v_mbcnt_lo_u32_b32 v1, s6, 0
	v_mbcnt_hi_u32_b32 v1, s7, v1
	v_cmp_eq_u32_e32 vcc, 0, v1
	s_and_saveexec_b64 s[8:9], vcc
	s_cbranch_execz .LBB0_985
	s_bcnt1_i32_b64 s6, s[6:7]
	v_mov_b32_e32 v2, 0x3000
	v_mov_b32_e32 v3, s6
	global_atomic_add v2, v2, v3, s[26:27] offset:1024 sc0

; __device__ __forceinline__ unsigned xb_add(unsigned* p, unsigned v) { return __hip_atomic_fetch_add(p, v, __ATOMIC_RELAXED, __HIP_MEMORY_SCOPE_AGENT); }
; __device__ __forceinline__ void xcd_barrier(const XcdBarrier& b) {
;     ...
;             __builtin_amdgcn_fence(__ATOMIC_ACQUIRE, "agent");
;             xb_add(&bar[XB_XGEN(b.x)], 1u);
.LBB0_999:
	s_or_b64 exec, exec, s[6:7]
	s_mov_b64 s[6:7], exec
	v_mbcnt_lo_u32_b32 v0, s6, 0
	v_mbcnt_hi_u32_b32 v0, s7, v0
	v_cmp_eq_u32_e32 vcc, 0, v0
	s_waitcnt vmcnt(0)
	s_and_saveexec_b64 s[8:9], vcc
	s_cbranch_execz .LBB0_1001
	s_bcnt1_i32_b64 s6, s[6:7]
	v_mov_b32_e32 v0, 0x2000
	v_mov_b32_e32 v1, s6
	global_atomic_add v0, v1, s[4:5] offset:1024
